# DA ring loop: running-max subtraction folded into the QK MFMA (SrcC = block holding -m), 17 fewer VALU per tile; downstream placement padded to match v23
# baseline (speedup 1.0000x reference)
.Lmy_pp_srcdone:
	v_mov_b32_e32 v245, 0
	v_add_u32_e32 v246, 0x10000, v150
	s_lshr_b32 s28, s25, 2
	s_lshl_b32 s28, s28, 12
	s_lshl_b32 s24, s25, 11
	s_add_i32 s24, s24, 0x10000
	v_add_u32_e32 v247, s28, v246
	s_mov_b32 m0, s24
	s_nop 0
	global_load_lds_dwordx4 v[242:243], off
	global_load_lds_dwordx4 v[242:243], off offset:1024
	v_lshl_add_u64 v[242:243], v[244:245], 0, v[242:243]
	s_add_i32 m0, s24, 0x4000
	s_nop 0
	global_load_lds_dwordx4 v[242:243], off
	global_load_lds_dwordx4 v[242:243], off offset:1024
	v_lshl_add_u64 v[242:243], v[244:245], 0, v[242:243]
	s_add_i32 m0, s24, 0x8000
	s_nop 0
	global_load_lds_dwordx4 v[242:243], off
	global_load_lds_dwordx4 v[242:243], off offset:1024
	v_lshl_add_u64 v[242:243], v[244:245], 0, v[242:243]
	s_add_i32 s24, s24, 0xc000
	s_lshr_b32 s29, s25, 2
	s_mov_b32 s25, 0
	s_mov_b32 s13, 71
	v_mov_b32_e32 v172, 0
	v_mov_b32_e32 v173, 0
	v_mov_b32_e32 v174, 0
	v_mov_b32_e32 v175, 0
	v_mov_b32_e32 v176, 0
	v_mov_b32_e32 v177, 0
	v_mov_b32_e32 v178, 0
	v_mov_b32_e32 v179, 0
	v_mov_b32_e32 v180, 0
	v_mov_b32_e32 v181, 0
	v_mov_b32_e32 v182, 0
	v_mov_b32_e32 v183, 0
	v_mov_b32_e32 v184, 0
	v_mov_b32_e32 v185, 0
	v_mov_b32_e32 v186, 0
	v_mov_b32_e32 v187, 0
	v_mov_b32_e32 v241, 0
	v_add_f32_e32 v214, 0x41000000, v208
	s_cmp_eq_u32 s29, 0
	s_cbranch_scc1 .Lmy_pp_noprio
	s_setprio 1

.Lmy_pp_loop2:
	v_add_u32_e32 v248, s25, v246
	v_add_u32_e32 v249, s25, v247
	ds_read_b128 v[144:147], v248 offset:8192
	ds_read_b128 v[136:139], v248 offset:10240
	ds_read_b128 v[132:135], v248 offset:12288
	ds_read_b128 v[116:119], v248 offset:14336
	ds_read_b128 v[128:131], v248 offset:9216
	ds_read_b128 v[140:143], v248 offset:11264
	ds_read_b128 v[124:127], v248 offset:13312
	ds_read_b128 v[120:123], v248 offset:15360
	v_max3_f32 v14, v80, v81, v82
	v_max3_f32 v15, v83, v84, v85
	v_max3_f32 v209, v86, v87, v88
	v_max3_f32 v212, v89, v90, v91
	v_max3_f32 v14, v14, v92, v93
	v_max3_f32 v15, v15, v94, v95
	v_max3_f32 v14, v14, v15, v209
	v_max_f32_e32 v14, v14, v212
	v_mov_b32_e32 v15, v14
	s_mov_b32 m0, s24
	s_sub_i32 s28, 5, s29
	s_cmp_gt_u32 s13, s28
	s_cselect_b32 s28, -1, 0
	v_permlane32_swap_b32_e32 v14, v15
	s_add_i32 s24, s24, 0x4000
	s_and_b32 s24, s24, 0xffff
	v_max_f32_e32 v14, v14, v15
	s_nop 0
	v_cmp_gt_f32_e32 vcc, v14, v214
	s_cbranch_vccz .Lmy_pp_nors_a
	v_add_f32_e32 v14, v241, v14
	v_max_f32_e32 v15, v208, v14
	v_sub_f32_e32 v14, v208, v15
	v_exp_f32_e32 v14, v14
	v_sub_f32_e32 v209, v241, v15
	v_mov_b32_e32 v208, v15
	v_mov_b32_e32 v241, v15
	v_mov_b32_e32 v214, 0x41000000
	v_mul_f32_e32 v0, v0, v14
	v_pk_mul_f32 v[78:79], v[78:79], v[14:15] op_sel_hi:[1,0]
	v_pk_mul_f32 v[76:77], v[76:77], v[14:15] op_sel_hi:[1,0]
	v_pk_mul_f32 v[74:75], v[74:75], v[14:15] op_sel_hi:[1,0]
	v_pk_mul_f32 v[72:73], v[72:73], v[14:15] op_sel_hi:[1,0]
	v_pk_mul_f32 v[70:71], v[70:71], v[14:15] op_sel_hi:[1,0]
	v_pk_mul_f32 v[68:69], v[68:69], v[14:15] op_sel_hi:[1,0]
	v_pk_mul_f32 v[66:67], v[66:67], v[14:15] op_sel_hi:[1,0]
	v_pk_mul_f32 v[64:65], v[64:65], v[14:15] op_sel_hi:[1,0]
	v_pk_mul_f32 v[62:63], v[62:63], v[14:15] op_sel_hi:[1,0]
	v_pk_mul_f32 v[60:61], v[60:61], v[14:15] op_sel_hi:[1,0]
	v_pk_mul_f32 v[58:59], v[58:59], v[14:15] op_sel_hi:[1,0]
	v_pk_mul_f32 v[56:57], v[56:57], v[14:15] op_sel_hi:[1,0]
	v_pk_mul_f32 v[54:55], v[54:55], v[14:15] op_sel_hi:[1,0]
	v_pk_mul_f32 v[52:53], v[52:53], v[14:15] op_sel_hi:[1,0]
	v_pk_mul_f32 v[50:51], v[50:51], v[14:15] op_sel_hi:[1,0]
	v_pk_mul_f32 v[48:49], v[48:49], v[14:15] op_sel_hi:[1,0]
	v_pk_mul_f32 v[46:47], v[46:47], v[14:15] op_sel_hi:[1,0]
	v_pk_mul_f32 v[44:45], v[44:45], v[14:15] op_sel_hi:[1,0]
	v_pk_mul_f32 v[42:43], v[42:43], v[14:15] op_sel_hi:[1,0]
	v_pk_mul_f32 v[40:41], v[40:41], v[14:15] op_sel_hi:[1,0]
	v_pk_mul_f32 v[38:39], v[38:39], v[14:15] op_sel_hi:[1,0]
	v_pk_mul_f32 v[36:37], v[36:37], v[14:15] op_sel_hi:[1,0]
	v_pk_mul_f32 v[34:35], v[34:35], v[14:15] op_sel_hi:[1,0]
	v_pk_mul_f32 v[32:33], v[32:33], v[14:15] op_sel_hi:[1,0]
	v_pk_mul_f32 v[30:31], v[30:31], v[14:15] op_sel_hi:[1,0]
	v_pk_mul_f32 v[28:29], v[28:29], v[14:15] op_sel_hi:[1,0]
	v_pk_mul_f32 v[26:27], v[26:27], v[14:15] op_sel_hi:[1,0]
	v_pk_mul_f32 v[24:25], v[24:25], v[14:15] op_sel_hi:[1,0]
	v_pk_mul_f32 v[22:23], v[22:23], v[14:15] op_sel_hi:[1,0]
	v_pk_mul_f32 v[20:21], v[20:21], v[14:15] op_sel_hi:[1,0]
	v_pk_mul_f32 v[18:19], v[18:19], v[14:15] op_sel_hi:[1,0]
	v_pk_mul_f32 v[16:17], v[16:17], v[14:15] op_sel_hi:[1,0]
	v_add_f32_e32 v80, v209, v80
	v_add_f32_e32 v81, v209, v81
	v_add_f32_e32 v82, v209, v82
	v_add_f32_e32 v83, v209, v83
	v_add_f32_e32 v84, v209, v84
	v_add_f32_e32 v85, v209, v85
	v_add_f32_e32 v86, v209, v86
	v_add_f32_e32 v87, v209, v87
	v_add_f32_e32 v88, v209, v88
	v_add_f32_e32 v89, v209, v89
	v_add_f32_e32 v90, v209, v90
	v_add_f32_e32 v91, v209, v91
	v_add_f32_e32 v92, v209, v92
	v_add_f32_e32 v93, v209, v93
	v_add_f32_e32 v94, v209, v94
	v_add_f32_e32 v95, v209, v95
	v_sub_f32_e32 v212, 0, v15
	v_mov_b32_e32 v172, v212
	v_mov_b32_e32 v173, v212
	v_mov_b32_e32 v174, v212
	v_mov_b32_e32 v175, v212
	v_mov_b32_e32 v176, v212
	v_mov_b32_e32 v177, v212
	v_mov_b32_e32 v178, v212
	v_mov_b32_e32 v179, v212
	v_mov_b32_e32 v180, v212
	v_mov_b32_e32 v181, v212
	v_mov_b32_e32 v182, v212
	v_mov_b32_e32 v183, v212
	v_mov_b32_e32 v184, v212
	v_mov_b32_e32 v185, v212
	v_mov_b32_e32 v186, v212
	v_mov_b32_e32 v187, v212
.Lmy_pp_nors_a:
	v_exp_f32_e32 v80, v80
	v_exp_f32_e32 v81, v81
	v_mfma_f32_32x32x16_bf16 v[218:233], v[112:115], v[108:111], v[172:187]
	v_exp_f32_e32 v82, v82
	v_exp_f32_e32 v83, v83
	v_mfma_f32_32x32x16_bf16 v[218:233], v[10:13], v[104:107], v[218:233]
	v_exp_f32_e32 v84, v84
	v_exp_f32_e32 v85, v85
	v_add_f32_e32 v15, 0, v80
	global_load_lds_dwordx4 v[242:243], off
	global_load_lds_dwordx4 v[242:243], off offset:1024
	v_mfma_f32_32x32x16_bf16 v[218:233], v[6:9], v[100:103], v[218:233]
	v_exp_f32_e32 v86, v86
	v_exp_f32_e32 v87, v87
	v_and_b32_e32 v244, s28, v244
	v_add_f32_e32 v15, v81, v15
	v_mfma_f32_32x32x16_bf16 v[218:233], v[2:5], v[96:99], v[218:233]
	v_add_f32_e32 v15, v82, v15
	v_lshl_add_u64 v[242:243], v[244:245], 0, v[242:243]
	s_or_b32 s24, s24, 0x10000
	s_cmp_eq_u32 s13, 69
	s_cbranch_scc0 .Lmy_pp_nsw_a
	s_cmp_lg_u32 s29, 0
	s_cbranch_scc1 .Lmy_pp_nsw_a
	v_mov_b32_e32 v242, v250
	v_mov_b32_e32 v243, v251
.Lmy_pp_nsw_a:
	ds_read_b128 v[112:115], v249
	ds_read_b128 v[10:13], v249 offset:1024
	ds_read_b128 v[6:9], v249 offset:2048
	ds_read_b128 v[2:5], v249 offset:3072
	s_add_i32 s25, s25, 0x4000
	s_and_b32 s25, s25, 0xc000
	v_add_f32_e32 v15, v83, v15
	v_add_f32_e32 v15, v84, v15
	v_add_f32_e32 v15, v85, v15
	v_add_f32_e32 v15, v86, v15
	v_add_f32_e32 v15, v87, v15
	v_cvt_pk_bf16_f32 v80, v80, v81
	v_cvt_pk_bf16_f32 v81, v82, v83
	v_cvt_pk_bf16_f32 v82, v84, v85
	v_cvt_pk_bf16_f32 v83, v86, v87
	v_exp_f32_e32 v88, v88
	v_exp_f32_e32 v89, v89
	s_waitcnt lgkmcnt(4)
	v_mfma_f32_32x32x16_bf16 v[64:79], v[144:147], v[80:83], v[64:79]
	v_exp_f32_e32 v90, v90
	v_exp_f32_e32 v91, v91
	v_exp_f32_e32 v92, v92
	v_mfma_f32_32x32x16_bf16 v[48:63], v[136:139], v[80:83], v[48:63]
	v_exp_f32_e32 v93, v93
	v_exp_f32_e32 v94, v94
	v_exp_f32_e32 v95, v95
	v_mfma_f32_32x32x16_bf16 v[32:47], v[132:135], v[80:83], v[32:47]
	v_add_f32_e32 v15, v88, v15
	v_add_f32_e32 v15, v89, v15
	v_add_f32_e32 v15, v90, v15
	v_add_f32_e32 v15, v91, v15
	v_mfma_f32_32x32x16_bf16 v[16:31], v[116:119], v[80:83], v[16:31]
	s_cmp_eq_u32 s29, 0
	s_cbranch_scc1 .Lmy_pp_nbm_a
	s_waitcnt vmcnt(4) lgkmcnt(0)
	s_barrier
.Lmy_pp_nbm_a:
	v_cvt_pk_bf16_f32 v84, v88, v89
	v_cvt_pk_bf16_f32 v85, v90, v91
	v_cvt_pk_bf16_f32 v86, v92, v93
	v_cvt_pk_bf16_f32 v87, v94, v95
	v_add_f32_e32 v15, v92, v15
	v_add_f32_e32 v15, v93, v15
	v_mfma_f32_32x32x16_bf16 v[64:79], v[128:131], v[84:87], v[64:79]
	v_add_f32_e32 v15, v94, v15
	v_add_f32_e32 v15, v95, v15
	s_add_i32 s13, s13, -1
	v_mfma_f32_32x32x16_bf16 v[48:63], v[140:143], v[84:87], v[48:63]
	v_add_f32_e32 v0, v0, v15
	v_mfma_f32_32x32x16_bf16 v[32:47], v[124:127], v[84:87], v[32:47]
	v_mfma_f32_32x32x16_bf16 v[16:31], v[120:123], v[84:87], v[16:31]
	s_cmp_lg_u32 s29, 0
	s_cbranch_scc1 .Lmy_pp_nbe_a
	s_waitcnt vmcnt(4) lgkmcnt(0)
	s_barrier
.Lmy_pp_nbe_a:
	v_add_u32_e32 v248, s25, v246
	v_add_u32_e32 v249, s25, v247
	ds_read_b128 v[144:147], v248 offset:8192
	ds_read_b128 v[136:139], v248 offset:10240
	ds_read_b128 v[132:135], v248 offset:12288
	ds_read_b128 v[116:119], v248 offset:14336
	ds_read_b128 v[128:131], v248 offset:9216
	ds_read_b128 v[140:143], v248 offset:11264
	ds_read_b128 v[124:127], v248 offset:13312
	ds_read_b128 v[120:123], v248 offset:15360
	v_max3_f32 v14, v218, v219, v220
	v_max3_f32 v15, v221, v222, v223
	v_max3_f32 v209, v224, v225, v226
	v_max3_f32 v212, v227, v228, v229
	v_max3_f32 v14, v14, v230, v231
	v_max3_f32 v15, v15, v232, v233
	v_max3_f32 v14, v14, v15, v209
	v_max_f32_e32 v14, v14, v212
	v_mov_b32_e32 v15, v14
	s_mov_b32 m0, s24
	s_sub_i32 s28, 5, s29
	s_cmp_gt_u32 s13, s28
	s_cselect_b32 s28, -1, 0
	v_permlane32_swap_b32_e32 v14, v15
	s_add_i32 s24, s24, 0x4000
	s_and_b32 s24, s24, 0xffff
	v_max_f32_e32 v14, v14, v15
	s_nop 0
	v_cmp_gt_f32_e32 vcc, v14, v214
	s_cbranch_vccz .Lmy_pp_nors_b
	v_add_f32_e32 v14, v241, v14
	v_max_f32_e32 v15, v208, v14
	v_sub_f32_e32 v14, v208, v15
	v_exp_f32_e32 v14, v14
	v_sub_f32_e32 v209, v241, v15
	v_mov_b32_e32 v208, v15
	v_mov_b32_e32 v241, v15
	v_mov_b32_e32 v214, 0x41000000
	v_mul_f32_e32 v0, v0, v14
	v_pk_mul_f32 v[78:79], v[78:79], v[14:15] op_sel_hi:[1,0]
	v_pk_mul_f32 v[76:77], v[76:77], v[14:15] op_sel_hi:[1,0]
	v_pk_mul_f32 v[74:75], v[74:75], v[14:15] op_sel_hi:[1,0]
	v_pk_mul_f32 v[72:73], v[72:73], v[14:15] op_sel_hi:[1,0]
	v_pk_mul_f32 v[70:71], v[70:71], v[14:15] op_sel_hi:[1,0]
	v_pk_mul_f32 v[68:69], v[68:69], v[14:15] op_sel_hi:[1,0]
	v_pk_mul_f32 v[66:67], v[66:67], v[14:15] op_sel_hi:[1,0]
	v_pk_mul_f32 v[64:65], v[64:65], v[14:15] op_sel_hi:[1,0]
	v_pk_mul_f32 v[62:63], v[62:63], v[14:15] op_sel_hi:[1,0]
	v_pk_mul_f32 v[60:61], v[60:61], v[14:15] op_sel_hi:[1,0]
	v_pk_mul_f32 v[58:59], v[58:59], v[14:15] op_sel_hi:[1,0]
	v_pk_mul_f32 v[56:57], v[56:57], v[14:15] op_sel_hi:[1,0]
	v_pk_mul_f32 v[54:55], v[54:55], v[14:15] op_sel_hi:[1,0]
	v_pk_mul_f32 v[52:53], v[52:53], v[14:15] op_sel_hi:[1,0]
	v_pk_mul_f32 v[50:51], v[50:51], v[14:15] op_sel_hi:[1,0]
	v_pk_mul_f32 v[48:49], v[48:49], v[14:15] op_sel_hi:[1,0]
	v_pk_mul_f32 v[46:47], v[46:47], v[14:15] op_sel_hi:[1,0]
	v_pk_mul_f32 v[44:45], v[44:45], v[14:15] op_sel_hi:[1,0]
	v_pk_mul_f32 v[42:43], v[42:43], v[14:15] op_sel_hi:[1,0]
	v_pk_mul_f32 v[40:41], v[40:41], v[14:15] op_sel_hi:[1,0]
	v_pk_mul_f32 v[38:39], v[38:39], v[14:15] op_sel_hi:[1,0]
	v_pk_mul_f32 v[36:37], v[36:37], v[14:15] op_sel_hi:[1,0]
	v_pk_mul_f32 v[34:35], v[34:35], v[14:15] op_sel_hi:[1,0]
	v_pk_mul_f32 v[32:33], v[32:33], v[14:15] op_sel_hi:[1,0]
	v_pk_mul_f32 v[30:31], v[30:31], v[14:15] op_sel_hi:[1,0]
	v_pk_mul_f32 v[28:29], v[28:29], v[14:15] op_sel_hi:[1,0]
	v_pk_mul_f32 v[26:27], v[26:27], v[14:15] op_sel_hi:[1,0]
	v_pk_mul_f32 v[24:25], v[24:25], v[14:15] op_sel_hi:[1,0]
	v_pk_mul_f32 v[22:23], v[22:23], v[14:15] op_sel_hi:[1,0]
	v_pk_mul_f32 v[20:21], v[20:21], v[14:15] op_sel_hi:[1,0]
	v_pk_mul_f32 v[18:19], v[18:19], v[14:15] op_sel_hi:[1,0]
	v_pk_mul_f32 v[16:17], v[16:17], v[14:15] op_sel_hi:[1,0]
	v_add_f32_e32 v218, v209, v218
	v_add_f32_e32 v219, v209, v219
	v_add_f32_e32 v220, v209, v220
	v_add_f32_e32 v221, v209, v221
	v_add_f32_e32 v222, v209, v222
	v_add_f32_e32 v223, v209, v223
	v_add_f32_e32 v224, v209, v224
	v_add_f32_e32 v225, v209, v225
	v_add_f32_e32 v226, v209, v226
	v_add_f32_e32 v227, v209, v227
	v_add_f32_e32 v228, v209, v228
	v_add_f32_e32 v229, v209, v229
	v_add_f32_e32 v230, v209, v230
	v_add_f32_e32 v231, v209, v231
	v_add_f32_e32 v232, v209, v232
	v_add_f32_e32 v233, v209, v233
	v_sub_f32_e32 v212, 0, v15
	v_mov_b32_e32 v172, v212
	v_mov_b32_e32 v173, v212
	v_mov_b32_e32 v174, v212
	v_mov_b32_e32 v175, v212
	v_mov_b32_e32 v176, v212
	v_mov_b32_e32 v177, v212
	v_mov_b32_e32 v178, v212
	v_mov_b32_e32 v179, v212
	v_mov_b32_e32 v180, v212
	v_mov_b32_e32 v181, v212
	v_mov_b32_e32 v182, v212
	v_mov_b32_e32 v183, v212
	v_mov_b32_e32 v184, v212
	v_mov_b32_e32 v185, v212
	v_mov_b32_e32 v186, v212
	v_mov_b32_e32 v187, v212
.Lmy_pp_nors_b:
	v_exp_f32_e32 v218, v218
	v_exp_f32_e32 v219, v219
	v_mfma_f32_32x32x16_bf16 v[80:95], v[112:115], v[108:111], v[172:187]
	v_exp_f32_e32 v220, v220
	v_exp_f32_e32 v221, v221
	v_mfma_f32_32x32x16_bf16 v[80:95], v[10:13], v[104:107], v[80:95]
	v_exp_f32_e32 v222, v222
	v_exp_f32_e32 v223, v223
	v_add_f32_e32 v15, 0, v218
	global_load_lds_dwordx4 v[242:243], off
	global_load_lds_dwordx4 v[242:243], off offset:1024
	v_mfma_f32_32x32x16_bf16 v[80:95], v[6:9], v[100:103], v[80:95]
	v_exp_f32_e32 v224, v224
	v_exp_f32_e32 v225, v225
	v_and_b32_e32 v244, s28, v244
	v_add_f32_e32 v15, v219, v15
	v_mfma_f32_32x32x16_bf16 v[80:95], v[2:5], v[96:99], v[80:95]
	v_add_f32_e32 v15, v220, v15
	v_lshl_add_u64 v[242:243], v[244:245], 0, v[242:243]
	s_or_b32 s24, s24, 0x10000
	s_cmp_eq_u32 s13, 69
	s_cbranch_scc0 .Lmy_pp_nsw_b
	s_cmp_lg_u32 s29, 0
	s_cbranch_scc1 .Lmy_pp_nsw_b
	v_mov_b32_e32 v242, v250
	v_mov_b32_e32 v243, v251
.Lmy_pp_nsw_b:
	ds_read_b128 v[112:115], v249
	ds_read_b128 v[10:13], v249 offset:1024
	ds_read_b128 v[6:9], v249 offset:2048
	ds_read_b128 v[2:5], v249 offset:3072
	s_add_i32 s25, s25, 0x4000
	s_and_b32 s25, s25, 0xc000
	v_add_f32_e32 v15, v221, v15
	v_add_f32_e32 v15, v222, v15
	v_add_f32_e32 v15, v223, v15
	v_add_f32_e32 v15, v224, v15
	v_add_f32_e32 v15, v225, v15
	v_cvt_pk_bf16_f32 v218, v218, v219
	v_cvt_pk_bf16_f32 v219, v220, v221
	v_cvt_pk_bf16_f32 v220, v222, v223
	v_cvt_pk_bf16_f32 v221, v224, v225
	v_exp_f32_e32 v226, v226
	v_exp_f32_e32 v227, v227
	s_waitcnt lgkmcnt(4)
	v_mfma_f32_32x32x16_bf16 v[64:79], v[144:147], v[218:221], v[64:79]
	v_exp_f32_e32 v228, v228
	v_exp_f32_e32 v229, v229
	v_exp_f32_e32 v230, v230
	v_mfma_f32_32x32x16_bf16 v[48:63], v[136:139], v[218:221], v[48:63]
	v_exp_f32_e32 v231, v231
	v_exp_f32_e32 v232, v232
	v_exp_f32_e32 v233, v233
	v_mfma_f32_32x32x16_bf16 v[32:47], v[132:135], v[218:221], v[32:47]
	v_add_f32_e32 v15, v226, v15
	v_add_f32_e32 v15, v227, v15
	v_add_f32_e32 v15, v228, v15
	v_add_f32_e32 v15, v229, v15
	v_mfma_f32_32x32x16_bf16 v[16:31], v[116:119], v[218:221], v[16:31]
	s_cmp_eq_u32 s29, 0
	s_cbranch_scc1 .Lmy_pp_nbm_b
	s_waitcnt vmcnt(4) lgkmcnt(0)
	s_barrier
.Lmy_pp_nbm_b:
	v_cvt_pk_bf16_f32 v222, v226, v227
	v_cvt_pk_bf16_f32 v223, v228, v229
	v_cvt_pk_bf16_f32 v224, v230, v231
	v_cvt_pk_bf16_f32 v225, v232, v233
	v_add_f32_e32 v15, v230, v15
	v_add_f32_e32 v15, v231, v15
	v_mfma_f32_32x32x16_bf16 v[64:79], v[128:131], v[222:225], v[64:79]
	v_add_f32_e32 v15, v232, v15
	v_add_f32_e32 v15, v233, v15
	s_add_i32 s13, s13, -1
	v_mfma_f32_32x32x16_bf16 v[48:63], v[140:143], v[222:225], v[48:63]
	v_add_f32_e32 v0, v0, v15
	v_mfma_f32_32x32x16_bf16 v[32:47], v[124:127], v[222:225], v[32:47]
	v_mfma_f32_32x32x16_bf16 v[16:31], v[120:123], v[222:225], v[16:31]
	s_cmp_lg_u32 s29, 0
	s_cbranch_scc1 .Lmy_pp_nbe_b
	s_waitcnt vmcnt(4) lgkmcnt(0)
	s_barrier
.Lmy_pp_nbe_b:
	s_cmp_gt_u32 s13, 1
	s_cbranch_scc1 .Lmy_pp_loop2
	v_add_u32_e32 v248, s25, v246
	v_add_u32_e32 v249, s25, v247
	ds_read_b128 v[144:147], v248 offset:8192
	ds_read_b128 v[136:139], v248 offset:10240
	ds_read_b128 v[132:135], v248 offset:12288
	ds_read_b128 v[116:119], v248 offset:14336
	ds_read_b128 v[128:131], v248 offset:9216
	ds_read_b128 v[140:143], v248 offset:11264
	ds_read_b128 v[124:127], v248 offset:13312
	ds_read_b128 v[120:123], v248 offset:15360
	v_max3_f32 v14, v80, v81, v82
	v_max3_f32 v15, v83, v84, v85
	v_max3_f32 v209, v86, v87, v88
	v_max3_f32 v212, v89, v90, v91
	v_max3_f32 v14, v14, v92, v93
	v_max3_f32 v15, v15, v94, v95
	v_max3_f32 v14, v14, v15, v209
	v_max_f32_e32 v14, v14, v212
	v_mov_b32_e32 v15, v14
	s_mov_b32 m0, s24
	s_sub_i32 s28, 5, s29
	s_cmp_gt_u32 s13, s28
	s_cselect_b32 s28, -1, 0
	v_permlane32_swap_b32_e32 v14, v15
	s_add_i32 s24, s24, 0x4000
	s_and_b32 s24, s24, 0xffff
	v_max_f32_e32 v14, v14, v15
	s_nop 0
	v_cmp_gt_f32_e32 vcc, v14, v214
	s_cbranch_vccz .Lmy_pp_nors_t
	v_add_f32_e32 v14, v241, v14
	v_max_f32_e32 v15, v208, v14
	v_sub_f32_e32 v14, v208, v15
	v_exp_f32_e32 v14, v14
	v_sub_f32_e32 v209, v241, v15
	v_mov_b32_e32 v208, v15
	v_mov_b32_e32 v241, v15
	v_mov_b32_e32 v214, 0x41000000
	v_mul_f32_e32 v0, v0, v14
	v_pk_mul_f32 v[78:79], v[78:79], v[14:15] op_sel_hi:[1,0]
	v_pk_mul_f32 v[76:77], v[76:77], v[14:15] op_sel_hi:[1,0]
	v_pk_mul_f32 v[74:75], v[74:75], v[14:15] op_sel_hi:[1,0]
	v_pk_mul_f32 v[72:73], v[72:73], v[14:15] op_sel_hi:[1,0]
	v_pk_mul_f32 v[70:71], v[70:71], v[14:15] op_sel_hi:[1,0]
	v_pk_mul_f32 v[68:69], v[68:69], v[14:15] op_sel_hi:[1,0]
	v_pk_mul_f32 v[66:67], v[66:67], v[14:15] op_sel_hi:[1,0]
	v_pk_mul_f32 v[64:65], v[64:65], v[14:15] op_sel_hi:[1,0]
	v_pk_mul_f32 v[62:63], v[62:63], v[14:15] op_sel_hi:[1,0]
	v_pk_mul_f32 v[60:61], v[60:61], v[14:15] op_sel_hi:[1,0]
	v_pk_mul_f32 v[58:59], v[58:59], v[14:15] op_sel_hi:[1,0]
	v_pk_mul_f32 v[56:57], v[56:57], v[14:15] op_sel_hi:[1,0]
	v_pk_mul_f32 v[54:55], v[54:55], v[14:15] op_sel_hi:[1,0]
	v_pk_mul_f32 v[52:53], v[52:53], v[14:15] op_sel_hi:[1,0]
	v_pk_mul_f32 v[50:51], v[50:51], v[14:15] op_sel_hi:[1,0]
	v_pk_mul_f32 v[48:49], v[48:49], v[14:15] op_sel_hi:[1,0]
	v_pk_mul_f32 v[46:47], v[46:47], v[14:15] op_sel_hi:[1,0]
	v_pk_mul_f32 v[44:45], v[44:45], v[14:15] op_sel_hi:[1,0]
	v_pk_mul_f32 v[42:43], v[42:43], v[14:15] op_sel_hi:[1,0]
	v_pk_mul_f32 v[40:41], v[40:41], v[14:15] op_sel_hi:[1,0]
	v_pk_mul_f32 v[38:39], v[38:39], v[14:15] op_sel_hi:[1,0]
	v_pk_mul_f32 v[36:37], v[36:37], v[14:15] op_sel_hi:[1,0]
	v_pk_mul_f32 v[34:35], v[34:35], v[14:15] op_sel_hi:[1,0]
	v_pk_mul_f32 v[32:33], v[32:33], v[14:15] op_sel_hi:[1,0]
	v_pk_mul_f32 v[30:31], v[30:31], v[14:15] op_sel_hi:[1,0]
	v_pk_mul_f32 v[28:29], v[28:29], v[14:15] op_sel_hi:[1,0]
	v_pk_mul_f32 v[26:27], v[26:27], v[14:15] op_sel_hi:[1,0]
	v_pk_mul_f32 v[24:25], v[24:25], v[14:15] op_sel_hi:[1,0]
	v_pk_mul_f32 v[22:23], v[22:23], v[14:15] op_sel_hi:[1,0]
	v_pk_mul_f32 v[20:21], v[20:21], v[14:15] op_sel_hi:[1,0]
	v_pk_mul_f32 v[18:19], v[18:19], v[14:15] op_sel_hi:[1,0]
	v_pk_mul_f32 v[16:17], v[16:17], v[14:15] op_sel_hi:[1,0]
	v_add_f32_e32 v80, v209, v80
	v_add_f32_e32 v81, v209, v81
	v_add_f32_e32 v82, v209, v82
	v_add_f32_e32 v83, v209, v83
	v_add_f32_e32 v84, v209, v84
	v_add_f32_e32 v85, v209, v85
	v_add_f32_e32 v86, v209, v86
	v_add_f32_e32 v87, v209, v87
	v_add_f32_e32 v88, v209, v88
	v_add_f32_e32 v89, v209, v89
	v_add_f32_e32 v90, v209, v90
	v_add_f32_e32 v91, v209, v91
	v_add_f32_e32 v92, v209, v92
	v_add_f32_e32 v93, v209, v93
	v_add_f32_e32 v94, v209, v94
	v_add_f32_e32 v95, v209, v95
	v_sub_f32_e32 v212, 0, v15
	v_mov_b32_e32 v172, v212
	v_mov_b32_e32 v173, v212
	v_mov_b32_e32 v174, v212
	v_mov_b32_e32 v175, v212
	v_mov_b32_e32 v176, v212
	v_mov_b32_e32 v177, v212
	v_mov_b32_e32 v178, v212
	v_mov_b32_e32 v179, v212
	v_mov_b32_e32 v180, v212
	v_mov_b32_e32 v181, v212
	v_mov_b32_e32 v182, v212
	v_mov_b32_e32 v183, v212
	v_mov_b32_e32 v184, v212
	v_mov_b32_e32 v185, v212
	v_mov_b32_e32 v186, v212
	v_mov_b32_e32 v187, v212

.Lmy_pp_nsw_t:
	s_add_i32 s25, s25, 0x4000
	s_and_b32 s25, s25, 0xc000
	v_add_f32_e32 v15, v83, v15
	v_add_f32_e32 v15, v84, v15
	v_add_f32_e32 v15, v85, v15
	v_add_f32_e32 v15, v86, v15
	v_add_f32_e32 v15, v87, v15
	v_cvt_pk_bf16_f32 v80, v80, v81
	v_cvt_pk_bf16_f32 v81, v82, v83
	v_cvt_pk_bf16_f32 v82, v84, v85
	v_cvt_pk_bf16_f32 v83, v86, v87
	v_exp_f32_e32 v88, v88
	v_exp_f32_e32 v89, v89
	s_waitcnt lgkmcnt(0)
	v_mfma_f32_32x32x16_bf16 v[64:79], v[144:147], v[80:83], v[64:79]
	v_exp_f32_e32 v90, v90
	v_exp_f32_e32 v91, v91
	v_exp_f32_e32 v92, v92
	v_mfma_f32_32x32x16_bf16 v[48:63], v[136:139], v[80:83], v[48:63]
	v_exp_f32_e32 v93, v93
	v_exp_f32_e32 v94, v94
	v_exp_f32_e32 v95, v95
	v_mfma_f32_32x32x16_bf16 v[32:47], v[132:135], v[80:83], v[32:47]
	v_add_f32_e32 v15, v88, v15
	v_add_f32_e32 v15, v89, v15
	v_add_f32_e32 v15, v90, v15
	v_add_f32_e32 v15, v91, v15
	v_mfma_f32_32x32x16_bf16 v[16:31], v[116:119], v[80:83], v[16:31]
	s_cmp_eq_u32 s29, 0
	s_cbranch_scc1 .Lmy_pp_nbm_t
	s_waitcnt vmcnt(4) lgkmcnt(0)
	s_barrier

.Lmy_pp_nbe_t:
	s_setprio 0
	v_lshl_add_u64 v[14:15], s[6:7], 0, v[150:151]
	s_mov_b64 s[28:29], 0xe58e000
	v_lshl_add_u64 v[172:173], v[14:15], 0, s[28:29]
	s_mov_b64 s[28:29], 0xe58e400
	v_lshl_add_u64 v[174:175], v[14:15], 0, s[28:29]
	s_mov_b64 s[28:29], 0xe58e800
	v_lshl_add_u64 v[176:177], v[14:15], 0, s[28:29]
	s_mov_b64 s[28:29], 0xe58ec00
	v_lshl_add_u64 v[178:179], v[14:15], 0, s[28:29]
	s_mov_b64 s[28:29], 0xe58f000
	v_lshl_add_u64 v[180:181], v[14:15], 0, s[28:29]
	s_mov_b64 s[28:29], 0xe58f400
	v_lshl_add_u64 v[182:183], v[14:15], 0, s[28:29]
	s_mov_b64 s[28:29], 0xe58f800
	v_lshl_add_u64 v[184:185], v[14:15], 0, s[28:29]
	s_mov_b64 s[28:29], 0xe58fc00
	v_lshl_add_u64 v[186:187], v[14:15], 0, s[28:29]

.LBB0_730:
	s_nop 0
	s_nop 0
	s_nop 0
	s_nop 0
	s_nop 0
	s_nop 0
	s_nop 0
	s_nop 0
	s_nop 0
	s_nop 0
	s_nop 0
	s_nop 0
	s_nop 0
	s_nop 0
	s_nop 0
	s_andn2_b64 vcc, exec, s[6:7]
	s_cbranch_vccnz .LBB0_732
	v_and_b32_e32 v185, 31, v240
	v_mov_b32_e32 v184, v204
